# diff loop: ALiBi tile base updated incrementally, no per-iteration key-position counter (3 fewer VALU ops per tile)
# baseline (speedup 1.0000x reference)
; __device__ __forceinline__ float shfl_xor_l(float v, int o, int lane) { return __builtin_bit_cast(float, __builtin_amdgcn_ds_bpermute((lane ^ o) << 2, __builtin_bit_cast(int, v))); }
; #define MX3(a, b, c) __builtin_fmaxf(__builtin_fmaxf((a), (b)), (c))
; template <int DQK, int DV, int FLAGS, int qp, int kp, int vts, int op> ...
;     ...
;             if (need_mask) {
; #pragma unroll
;                 for (int r = 0; r < 16; ++r) { const int c = 16 * (r >> 3) + (r & 7);
;                     bool m0 = false, m1 = false;
;                     if (FLAGS & AF_CAUSAL) { m0 = m0 || (c > nrel); m1 = m1 || (c + 32 > nrel); }
;                     if (FLAGS & AF_WINDOW) { m0 = m0 || (c <= nrel - SWA_W); m1 = m1 || (c + 32 <= nrel - SWA_W); }
;                     if (m0) p0[r] = -INFINITY; if (m1) p1[r] = -INFINITY; }
;             }
;             float mx = 0.f;
;             if ((FLAGS & AF_ROBUST) || !started || !skipmax) {
;               float a = MX3(p0[0], p0[1], p1[0]), b = MX3(p0[2], p0[3], p1[1]); a = MX3(a, p1[2], p1[3]);
; #pragma unroll
;               for (int r = 4; r < 16; r += 4) { a = MX3(a, p0[r], p0[r + 1]); b = MX3(b, p0[r + 2], p0[r + 3]); a = MX3(a, p1[r], p1[r + 1]); b = MX3(b, p1[r + 2], p1[r + 3]); }
;               mx = __builtin_fmaxf(a, b);
;               if ((FLAGS & AF_ROBUST) || !started) mx = __builtin_fmaxf(mx, shfl_xor_l(mx, 32, lane)); }
;             if (FLAGS & AF_ROBUST) {
;                 if (__any(mx > m + 8.0f)) {
;                     const float mn = fmaxf(m, mx), alpha = __builtin_amdgcn_exp2f(m - mn);
;                     l *= alpha; m = mn;
; #pragma unroll
;                     for (int d = 0; d < NDB; ++d)
; #pragma unroll
;                         for (int r = 0; r < 16; ++r) o[d][r] *= alpha;
;                 }
; #pragma unroll
;                 for (int r = 0; r < 16; ++r) { p0[r] -= m; p1[r] -= m; }
;             } else {
;                 if (!started) {
;                     started = true;
;                     m = mx;
; #pragma unroll
;                     for (int r = 0; r < 16; ++r) { p0[r] -= mx; p1[r] -= mx; }
.Ld_nopv_q0:
	s_cmp_lt_i32 s23, s24
	s_cbranch_scc1 .Ld_nosm_q0
	s_nop 7
	s_nop 7
	s_cmp_lg_u32 s23, s24
	s_cbranch_scc1 .Ld_notfirst_q0
	v_lshl_add_u32 v247, s23, 6, v205
	v_cmp_gt_i32_e64 s[46:47], 0, v247
	v_cmp_gt_i32_e64 s[48:49], 1, v247
	v_cmp_gt_i32_e64 s[50:51], 2, v247
	v_cmp_gt_i32_e64 s[52:53], 3, v247
	v_cndmask_b32_e64 v80, v80, v220, s[46:47]
	v_cmp_gt_i32_e64 s[46:47], 4, v247
	v_cndmask_b32_e64 v81, v81, v220, s[48:49]
	v_cmp_gt_i32_e64 s[48:49], 5, v247
	v_cndmask_b32_e64 v82, v82, v220, s[50:51]
	v_cmp_gt_i32_e64 s[50:51], 6, v247
	v_cndmask_b32_e64 v83, v83, v220, s[52:53]
	v_cmp_gt_i32_e64 s[52:53], 7, v247
	v_cndmask_b32_e64 v84, v84, v220, s[46:47]
	v_cmp_gt_i32_e64 s[46:47], 16, v247
	v_cndmask_b32_e64 v85, v85, v220, s[48:49]
	v_cmp_gt_i32_e64 s[48:49], 17, v247
	v_cndmask_b32_e64 v86, v86, v220, s[50:51]
	v_cmp_gt_i32_e64 s[50:51], 18, v247
	v_cndmask_b32_e64 v87, v87, v220, s[52:53]
	v_cmp_gt_i32_e64 s[52:53], 19, v247
	v_cndmask_b32_e64 v88, v88, v220, s[46:47]
	v_cmp_gt_i32_e64 s[46:47], 20, v247
	v_cndmask_b32_e64 v89, v89, v220, s[48:49]
	v_cmp_gt_i32_e64 s[48:49], 21, v247
	v_cndmask_b32_e64 v90, v90, v220, s[50:51]
	v_cmp_gt_i32_e64 s[50:51], 22, v247
	v_cndmask_b32_e64 v91, v91, v220, s[52:53]
	v_cmp_gt_i32_e64 s[52:53], 23, v247
	v_cndmask_b32_e64 v92, v92, v220, s[46:47]
	v_cmp_gt_i32_e64 s[46:47], 32, v247
	v_cndmask_b32_e64 v93, v93, v220, s[48:49]
	v_cmp_gt_i32_e64 s[48:49], 33, v247
	v_cndmask_b32_e64 v94, v94, v220, s[50:51]
	v_cmp_gt_i32_e64 s[50:51], 34, v247
	v_cndmask_b32_e64 v95, v95, v220, s[52:53]
	v_cmp_gt_i32_e64 s[52:53], 35, v247
	v_cndmask_b32_e64 v96, v96, v220, s[46:47]
	v_cmp_gt_i32_e64 s[46:47], 36, v247
	v_cndmask_b32_e64 v97, v97, v220, s[48:49]
	v_cmp_gt_i32_e64 s[48:49], 37, v247
	v_cndmask_b32_e64 v98, v98, v220, s[50:51]
	v_cmp_gt_i32_e64 s[50:51], 38, v247
	v_cndmask_b32_e64 v99, v99, v220, s[52:53]
	v_cmp_gt_i32_e64 s[52:53], 39, v247
	v_cndmask_b32_e64 v100, v100, v220, s[46:47]
	v_cmp_gt_i32_e64 s[46:47], 48, v247
	v_cndmask_b32_e64 v101, v101, v220, s[48:49]
	v_cmp_gt_i32_e64 s[48:49], 49, v247
	v_cndmask_b32_e64 v102, v102, v220, s[50:51]
	v_cmp_gt_i32_e64 s[50:51], 50, v247
	v_cndmask_b32_e64 v103, v103, v220, s[52:53]
	v_cmp_gt_i32_e64 s[52:53], 51, v247
	v_cndmask_b32_e64 v104, v104, v220, s[46:47]
	v_cmp_gt_i32_e64 s[46:47], 52, v247
	v_cndmask_b32_e64 v105, v105, v220, s[48:49]
	v_cmp_gt_i32_e64 s[48:49], 53, v247
	v_cndmask_b32_e64 v106, v106, v220, s[50:51]
	v_cmp_gt_i32_e64 s[50:51], 54, v247
	v_cndmask_b32_e64 v107, v107, v220, s[52:53]
	v_cmp_gt_i32_e64 s[52:53], 55, v247
	v_cndmask_b32_e64 v108, v108, v220, s[46:47]
	v_cndmask_b32_e64 v109, v109, v220, s[48:49]
	v_cndmask_b32_e64 v110, v110, v220, s[50:51]
	v_cndmask_b32_e64 v111, v111, v220, s[52:53]
	v_max3_f32 v246, v80, v81, v82
	v_max3_f32 v247, v96, v97, v98
	v_max3_f32 v246, v246, v83, v84
	v_max3_f32 v247, v247, v99, v100
	v_max3_f32 v246, v246, v85, v86
	v_max3_f32 v247, v247, v101, v102
	v_max3_f32 v246, v246, v87, v88
	v_max3_f32 v247, v247, v103, v104
	v_max3_f32 v246, v246, v89, v90
	v_max3_f32 v247, v247, v105, v106
	v_max3_f32 v246, v246, v91, v92
	v_max3_f32 v247, v247, v107, v108
	v_max3_f32 v246, v246, v93, v94
	v_max3_f32 v247, v247, v109, v110
	v_max3_f32 v246, v246, v95, v111
	v_max_f32_e32 v246, v246, v247
	s_nop 1
	ds_bpermute_b32 v247, v195, v246
	s_waitcnt lgkmcnt(0)
	v_max_f32_e32 v222, v246, v247
	v_sub_f32_e32 v80, v80, v222
	v_sub_f32_e32 v96, v96, v222
	v_sub_f32_e32 v81, v81, v222
	v_sub_f32_e32 v97, v97, v222
	v_sub_f32_e32 v82, v82, v222
	v_sub_f32_e32 v98, v98, v222
	v_sub_f32_e32 v83, v83, v222
	v_sub_f32_e32 v99, v99, v222
	v_sub_f32_e32 v84, v84, v222
	v_sub_f32_e32 v100, v100, v222
	v_sub_f32_e32 v85, v85, v222
	v_sub_f32_e32 v101, v101, v222
	v_sub_f32_e32 v86, v86, v222
	v_sub_f32_e32 v102, v102, v222
	v_sub_f32_e32 v87, v87, v222
	v_sub_f32_e32 v103, v103, v222
	v_sub_f32_e32 v88, v88, v222
	v_sub_f32_e32 v104, v104, v222
	v_sub_f32_e32 v89, v89, v222
	v_sub_f32_e32 v105, v105, v222
	v_sub_f32_e32 v90, v90, v222
	v_sub_f32_e32 v106, v106, v222
	v_sub_f32_e32 v91, v91, v222
	v_sub_f32_e32 v107, v107, v222
	v_sub_f32_e32 v92, v92, v222
	v_sub_f32_e32 v108, v108, v222
	v_sub_f32_e32 v93, v93, v222
	v_sub_f32_e32 v109, v109, v222
	v_sub_f32_e32 v94, v94, v222
	v_sub_f32_e32 v110, v110, v222
	v_sub_f32_e32 v95, v95, v222
	v_sub_f32_e32 v111, v111, v222

; #define LAS __attribute__((address_space(3)))
; template <int DQK, int DV, int FLAGS, int qp, int kp, int vts, int op> ...
;     ...
;             const LAS unsigned char* kb = lds + cur * BUF + prow * KROW + 16 * hi;
;             const LAS unsigned char* vb = lds + cur * BUF + KT_BYTES + r32 * VROW + 16 * hi;
;             f32x16 p0, p1;
;             bf16x8 kf[2][4];
; #pragma unroll
;             for (int i = 0; i < 2; ++i) { kf[0][2 * i] = *(const LAS bf16x8*)(kb + i * 32); kf[0][2 * i + 1] = *(const LAS bf16x8*)(kb + 32 * KROW + i * 32); }
;             const int nrel = qpos - kv0 - 8 * hi;
;             if (FLAGS & AF_ALIBI) { const float ab = -slope2 * (float)nrel - ((FLAGS & AF_ROBUST) ? 0.f : m);
; #pragma unroll
;                 for (int r = 0; r < 16; ++r) { const float c = (float)(16 * (r >> 3) + (r & 7)); p0[r] = __builtin_fmaf(slope2, c, ab); p1[r] = __builtin_fmaf(slope2, c + 32.f, ab); }
;             } else if (FLAGS & AF_ROBUST) {
; #pragma unroll
;                 for (int r = 0; r < 16; ++r) { p0[r] = 0.f; p1[r] = 0.f; }
;             } else { p0 = negm; p1 = negm; }
;             __builtin_amdgcn_sched_barrier(0);
; #pragma unroll
;             for (int c = 0; c < ND0 / 2; ++c) {
;                 if (c + 1 < ND0 / 2) {
; #pragma unroll
;                     for (int i = 0; i < 2; ++i) { kf[(c + 1) & 1][2 * i] = *(const LAS bf16x8*)(kb + (2 * c + 2 + i) * 32); kf[(c + 1) & 1][2 * i + 1] = *(const LAS bf16x8*)(kb + 32 * KROW + (2 * c + 2 + i) * 32); }
;                 }
; #pragma unroll
;                 for (int i = 0; i < 2; ++i) {
;                     p0 = __builtin_amdgcn_mfma_f32_32x32x16_bf16(kf[c & 1][2 * i], qr[2 * c + i], p0, 0, 0, 0);
;                     p1 = __builtin_amdgcn_mfma_f32_32x32x16_bf16(kf[c & 1][2 * i + 1], qr[2 * c + i], p1, 0, 0, 0);
;                 }
.Ld_nosm_q0:
	s_add_i32 s13, s23, 1
	s_cmp_ge_i32 s13, s3
	s_cbranch_scc1 .Ld_noqk_q0
	s_cmp_lt_i32 s13, s24
	s_cbranch_scc1 .Ld_noqk_q0
	s_add_i32 s12, s23, 1
	s_and_b32 s12, s12, 3
	s_mulk_i32 s12, 0x6c00
	v_add3_u32 v247, s12, v201, v194
	ds_read_b128 v[160:163], v247 offset:0
	ds_read_b128 v[164:167], v247 offset:32
	ds_read_b128 v[168:171], v247 offset:64
	ds_read_b128 v[172:175], v247 offset:96
	ds_read_b128 v[224:227], v247 offset:4608
	ds_read_b128 v[228:231], v247 offset:4640
	ds_read_b128 v[232:235], v247 offset:4672
	ds_read_b128 v[236:239], v247 offset:4704
	v_lshl_add_u32 v246, s13, 6, v205
	v_cvt_f32_i32_e32 v246, v246
	v_fma_f32 v242, -v14, v246, -v222
	v_mov_b32_e32 v112, v242
	v_add_f32_e32 v113, v14, v242
	v_fma_f32 v114, v14, s62, v242
	v_fma_f32 v115, v14, s63, v242
	v_fma_f32 v116, v14, s64, v242
	v_fma_f32 v117, v14, s65, v242
	v_fma_f32 v118, v14, s66, v242
	v_fma_f32 v119, v14, s67, v242
	v_fma_f32 v120, v14, s68, v242
	v_fma_f32 v121, v14, s69, v242
	v_fma_f32 v122, v14, s70, v242
	v_fma_f32 v123, v14, s71, v242
	v_fma_f32 v124, v14, s72, v242
	v_fma_f32 v125, v14, s73, v242
	v_fma_f32 v126, v14, s76, v242
	v_fma_f32 v127, v14, s77, v242
	v_fma_f32 v128, v14, s8, v242
	v_fma_f32 v129, v14, s9, v242
	v_fma_f32 v130, v14, s96, v242
	v_fma_f32 v131, v14, s97, v242
	v_fma_f32 v132, v14, s94, v242
	v_fma_f32 v133, v14, s95, v242
	v_fma_f32 v134, v14, s92, v242
	v_fma_f32 v135, v14, s93, v242
	v_fma_f32 v136, v14, s90, v242
	v_fma_f32 v137, v14, s91, v242
	v_fma_f32 v138, v14, s88, v242
	v_fma_f32 v139, v14, s89, v242
	v_fma_f32 v140, v14, s86, v242
	v_fma_f32 v141, v14, s87, v242
	v_fma_f32 v142, v14, s78, v242
	v_fma_f32 v143, v14, s79, v242
	s_waitcnt lgkmcnt(0)
	v_mfma_f32_32x32x16_bf16 v[112:127], v[160:163], v[2:5], v[112:127]
	v_mfma_f32_32x32x16_bf16 v[128:143], v[224:227], v[2:5], v[128:143]
	v_mfma_f32_32x32x16_bf16 v[112:127], v[164:167], v[6:9], v[112:127]
	v_mfma_f32_32x32x16_bf16 v[128:143], v[228:231], v[6:9], v[128:143]
	v_mfma_f32_32x32x16_bf16 v[112:127], v[168:171], v[10:13], v[112:127]
	v_mfma_f32_32x32x16_bf16 v[128:143], v[232:235], v[10:13], v[128:143]
	v_mfma_f32_32x32x16_bf16 v[112:127], v[172:175], v[144:147], v[112:127]
	v_mfma_f32_32x32x16_bf16 v[128:143], v[236:239], v[144:147], v[128:143]

; #define ATT_LSTORE(buf) do { LAS unsigned char* b_ = lds + (buf) * BUF; \
;         _Pragma("unroll") for (int i = 0; i < KPT; ++i) { if (KCH % NTHREADS == 0 || tid + i * NTHREADS < KCH) *(LAS u32x4*)(b_ + klo[i]) = kreg[i]; } \
;         _Pragma("unroll") for (int i = 0; i < VPT; ++i) *(LAS u32x4*)(b_ + vlo[i]) = vreg[i]; } while (0)
; template <int DQK, int DV, int FLAGS, int qp, int kp, int vts, int op> ...
;     ...
;     for (int it = 0; it < ntile; ++it) {
;         const int t = (FLAGS & AF_REV) ? kt_hi - 1 - it : kt_lo + it;
;         const int cur = it & 1;
;         const bool more = (it + 1 < ntile);
;         const int kv0 = t * 64;
;     ...
;         if (more) ATT_LSTORE(cur ^ 1);
;         __syncthreads();
.Ld_nopre_q0:
.Ld_tail0:
	s_add_i32 s23, s23, 1
	s_cmp_ge_i32 s23, s3
	s_cbranch_scc1 .Ld_flush1
	s_waitcnt lgkmcnt(0)
	s_barrier

; __device__ __forceinline__ float shfl_xor_l(float v, int o, int lane) { return __builtin_bit_cast(float, __builtin_amdgcn_ds_bpermute((lane ^ o) << 2, __builtin_bit_cast(int, v))); }
; #define MX3(a, b, c) __builtin_fmaxf(__builtin_fmaxf((a), (b)), (c))
; template <int DQK, int DV, int FLAGS, int qp, int kp, int vts, int op> ...
;     ...
;             if (need_mask) {
; #pragma unroll
;                 for (int r = 0; r < 16; ++r) { const int c = 16 * (r >> 3) + (r & 7);
;                     bool m0 = false, m1 = false;
;                     if (FLAGS & AF_CAUSAL) { m0 = m0 || (c > nrel); m1 = m1 || (c + 32 > nrel); }
;                     if (FLAGS & AF_WINDOW) { m0 = m0 || (c <= nrel - SWA_W); m1 = m1 || (c + 32 <= nrel - SWA_W); }
;                     if (m0) p0[r] = -INFINITY; if (m1) p1[r] = -INFINITY; }
;             }
;             float mx = 0.f;
;             if ((FLAGS & AF_ROBUST) || !started || !skipmax) {
;               float a = MX3(p0[0], p0[1], p1[0]), b = MX3(p0[2], p0[3], p1[1]); a = MX3(a, p1[2], p1[3]);
; #pragma unroll
;               for (int r = 4; r < 16; r += 4) { a = MX3(a, p0[r], p0[r + 1]); b = MX3(b, p0[r + 2], p0[r + 3]); a = MX3(a, p1[r], p1[r + 1]); b = MX3(b, p1[r + 2], p1[r + 3]); }
;               mx = __builtin_fmaxf(a, b);
;               if ((FLAGS & AF_ROBUST) || !started) mx = __builtin_fmaxf(mx, shfl_xor_l(mx, 32, lane)); }
;             if (FLAGS & AF_ROBUST) {
;                 if (__any(mx > m + 8.0f)) {
;                     const float mn = fmaxf(m, mx), alpha = __builtin_amdgcn_exp2f(m - mn);
;                     l *= alpha; m = mn;
; #pragma unroll
;                     for (int d = 0; d < NDB; ++d)
; #pragma unroll
;                         for (int r = 0; r < 16; ++r) o[d][r] *= alpha;
;                 }
; #pragma unroll
;                 for (int r = 0; r < 16; ++r) { p0[r] -= m; p1[r] -= m; }
;             } else {
;                 if (!started) {
;                     started = true;
;                     m = mx;
; #pragma unroll
;                     for (int r = 0; r < 16; ++r) { p0[r] -= mx; p1[r] -= mx; }
.Ld_nopv_q1:
	s_cmp_lt_i32 s23, s24
	s_cbranch_scc1 .Ld_nosm_q1
	s_nop 7
	s_nop 7
	s_cmp_lg_u32 s23, s24
	s_cbranch_scc1 .Ld_notfirst_q1
	v_lshl_add_u32 v247, s23, 6, v205
	v_cmp_gt_i32_e64 s[46:47], 0, v247
	v_cmp_gt_i32_e64 s[48:49], 1, v247
	v_cmp_gt_i32_e64 s[50:51], 2, v247
	v_cmp_gt_i32_e64 s[52:53], 3, v247
	v_cndmask_b32_e64 v112, v112, v220, s[46:47]
	v_cmp_gt_i32_e64 s[46:47], 4, v247
	v_cndmask_b32_e64 v113, v113, v220, s[48:49]
	v_cmp_gt_i32_e64 s[48:49], 5, v247
	v_cndmask_b32_e64 v114, v114, v220, s[50:51]
	v_cmp_gt_i32_e64 s[50:51], 6, v247
	v_cndmask_b32_e64 v115, v115, v220, s[52:53]
	v_cmp_gt_i32_e64 s[52:53], 7, v247
	v_cndmask_b32_e64 v116, v116, v220, s[46:47]
	v_cmp_gt_i32_e64 s[46:47], 16, v247
	v_cndmask_b32_e64 v117, v117, v220, s[48:49]
	v_cmp_gt_i32_e64 s[48:49], 17, v247
	v_cndmask_b32_e64 v118, v118, v220, s[50:51]
	v_cmp_gt_i32_e64 s[50:51], 18, v247
	v_cndmask_b32_e64 v119, v119, v220, s[52:53]
	v_cmp_gt_i32_e64 s[52:53], 19, v247
	v_cndmask_b32_e64 v120, v120, v220, s[46:47]
	v_cmp_gt_i32_e64 s[46:47], 20, v247
	v_cndmask_b32_e64 v121, v121, v220, s[48:49]
	v_cmp_gt_i32_e64 s[48:49], 21, v247
	v_cndmask_b32_e64 v122, v122, v220, s[50:51]
	v_cmp_gt_i32_e64 s[50:51], 22, v247
	v_cndmask_b32_e64 v123, v123, v220, s[52:53]
	v_cmp_gt_i32_e64 s[52:53], 23, v247
	v_cndmask_b32_e64 v124, v124, v220, s[46:47]
	v_cmp_gt_i32_e64 s[46:47], 32, v247
	v_cndmask_b32_e64 v125, v125, v220, s[48:49]
	v_cmp_gt_i32_e64 s[48:49], 33, v247
	v_cndmask_b32_e64 v126, v126, v220, s[50:51]
	v_cmp_gt_i32_e64 s[50:51], 34, v247
	v_cndmask_b32_e64 v127, v127, v220, s[52:53]
	v_cmp_gt_i32_e64 s[52:53], 35, v247
	v_cndmask_b32_e64 v128, v128, v220, s[46:47]
	v_cmp_gt_i32_e64 s[46:47], 36, v247
	v_cndmask_b32_e64 v129, v129, v220, s[48:49]
	v_cmp_gt_i32_e64 s[48:49], 37, v247
	v_cndmask_b32_e64 v130, v130, v220, s[50:51]
	v_cmp_gt_i32_e64 s[50:51], 38, v247
	v_cndmask_b32_e64 v131, v131, v220, s[52:53]
	v_cmp_gt_i32_e64 s[52:53], 39, v247
	v_cndmask_b32_e64 v132, v132, v220, s[46:47]
	v_cmp_gt_i32_e64 s[46:47], 48, v247
	v_cndmask_b32_e64 v133, v133, v220, s[48:49]
	v_cmp_gt_i32_e64 s[48:49], 49, v247
	v_cndmask_b32_e64 v134, v134, v220, s[50:51]
	v_cmp_gt_i32_e64 s[50:51], 50, v247
	v_cndmask_b32_e64 v135, v135, v220, s[52:53]
	v_cmp_gt_i32_e64 s[52:53], 51, v247
	v_cndmask_b32_e64 v136, v136, v220, s[46:47]
	v_cmp_gt_i32_e64 s[46:47], 52, v247
	v_cndmask_b32_e64 v137, v137, v220, s[48:49]
	v_cmp_gt_i32_e64 s[48:49], 53, v247
	v_cndmask_b32_e64 v138, v138, v220, s[50:51]
	v_cmp_gt_i32_e64 s[50:51], 54, v247
	v_cndmask_b32_e64 v139, v139, v220, s[52:53]
	v_cmp_gt_i32_e64 s[52:53], 55, v247
	v_cndmask_b32_e64 v140, v140, v220, s[46:47]
	v_cndmask_b32_e64 v141, v141, v220, s[48:49]
	v_cndmask_b32_e64 v142, v142, v220, s[50:51]
	v_cndmask_b32_e64 v143, v143, v220, s[52:53]
	v_max3_f32 v246, v112, v113, v114
	v_max3_f32 v247, v128, v129, v130
	v_max3_f32 v246, v246, v115, v116
	v_max3_f32 v247, v247, v131, v132
	v_max3_f32 v246, v246, v117, v118
	v_max3_f32 v247, v247, v133, v134
	v_max3_f32 v246, v246, v119, v120
	v_max3_f32 v247, v247, v135, v136
	v_max3_f32 v246, v246, v121, v122
	v_max3_f32 v247, v247, v137, v138
	v_max3_f32 v246, v246, v123, v124
	v_max3_f32 v247, v247, v139, v140
	v_max3_f32 v246, v246, v125, v126
	v_max3_f32 v247, v247, v141, v142
	v_max3_f32 v246, v246, v127, v143
	v_max_f32_e32 v246, v246, v247
	s_nop 1
	ds_bpermute_b32 v247, v195, v246
	s_waitcnt lgkmcnt(0)
	v_max_f32_e32 v222, v246, v247
	v_sub_f32_e32 v112, v112, v222
	v_sub_f32_e32 v128, v128, v222
	v_sub_f32_e32 v113, v113, v222
	v_sub_f32_e32 v129, v129, v222
	v_sub_f32_e32 v114, v114, v222
	v_sub_f32_e32 v130, v130, v222
	v_sub_f32_e32 v115, v115, v222
	v_sub_f32_e32 v131, v131, v222
	v_sub_f32_e32 v116, v116, v222
	v_sub_f32_e32 v132, v132, v222
	v_sub_f32_e32 v117, v117, v222
	v_sub_f32_e32 v133, v133, v222
	v_sub_f32_e32 v118, v118, v222
	v_sub_f32_e32 v134, v134, v222
	v_sub_f32_e32 v119, v119, v222
	v_sub_f32_e32 v135, v135, v222
	v_sub_f32_e32 v120, v120, v222
	v_sub_f32_e32 v136, v136, v222
	v_sub_f32_e32 v121, v121, v222
	v_sub_f32_e32 v137, v137, v222
	v_sub_f32_e32 v122, v122, v222
	v_sub_f32_e32 v138, v138, v222
	v_sub_f32_e32 v123, v123, v222
	v_sub_f32_e32 v139, v139, v222
	v_sub_f32_e32 v124, v124, v222
	v_sub_f32_e32 v140, v140, v222
	v_sub_f32_e32 v125, v125, v222
	v_sub_f32_e32 v141, v141, v222
	v_sub_f32_e32 v126, v126, v222
	v_sub_f32_e32 v142, v142, v222
	v_sub_f32_e32 v127, v127, v222
	v_sub_f32_e32 v143, v143, v222

; #define LAS __attribute__((address_space(3)))
; template <int DQK, int DV, int FLAGS, int qp, int kp, int vts, int op> ...
;     ...
;             const LAS unsigned char* kb = lds + cur * BUF + prow * KROW + 16 * hi;
;             const LAS unsigned char* vb = lds + cur * BUF + KT_BYTES + r32 * VROW + 16 * hi;
;             f32x16 p0, p1;
;             bf16x8 kf[2][4];
; #pragma unroll
;             for (int i = 0; i < 2; ++i) { kf[0][2 * i] = *(const LAS bf16x8*)(kb + i * 32); kf[0][2 * i + 1] = *(const LAS bf16x8*)(kb + 32 * KROW + i * 32); }
;             const int nrel = qpos - kv0 - 8 * hi;
;             if (FLAGS & AF_ALIBI) { const float ab = -slope2 * (float)nrel - ((FLAGS & AF_ROBUST) ? 0.f : m);
; #pragma unroll
;                 for (int r = 0; r < 16; ++r) { const float c = (float)(16 * (r >> 3) + (r & 7)); p0[r] = __builtin_fmaf(slope2, c, ab); p1[r] = __builtin_fmaf(slope2, c + 32.f, ab); }
;             } else if (FLAGS & AF_ROBUST) {
; #pragma unroll
;                 for (int r = 0; r < 16; ++r) { p0[r] = 0.f; p1[r] = 0.f; }
;             } else { p0 = negm; p1 = negm; }
;             __builtin_amdgcn_sched_barrier(0);
; #pragma unroll
;             for (int c = 0; c < ND0 / 2; ++c) {
;                 if (c + 1 < ND0 / 2) {
; #pragma unroll
;                     for (int i = 0; i < 2; ++i) { kf[(c + 1) & 1][2 * i] = *(const LAS bf16x8*)(kb + (2 * c + 2 + i) * 32); kf[(c + 1) & 1][2 * i + 1] = *(const LAS bf16x8*)(kb + 32 * KROW + (2 * c + 2 + i) * 32); }
;                 }
; #pragma unroll
;                 for (int i = 0; i < 2; ++i) {
;                     p0 = __builtin_amdgcn_mfma_f32_32x32x16_bf16(kf[c & 1][2 * i], qr[2 * c + i], p0, 0, 0, 0);
;                     p1 = __builtin_amdgcn_mfma_f32_32x32x16_bf16(kf[c & 1][2 * i + 1], qr[2 * c + i], p1, 0, 0, 0);
;                 }
.Ld_nosm_q1:
	s_add_i32 s13, s23, 1
	s_cmp_ge_i32 s13, s3
	s_cbranch_scc1 .Ld_noqk_q1
	s_cmp_lt_i32 s13, s24
	s_cbranch_scc1 .Ld_noqk_q1
	s_add_i32 s12, s23, 1
	s_and_b32 s12, s12, 3
	s_mulk_i32 s12, 0x6c00
	v_add3_u32 v247, s12, v201, v194
	ds_read_b128 v[160:163], v247 offset:0
	ds_read_b128 v[164:167], v247 offset:32
	ds_read_b128 v[168:171], v247 offset:64
	ds_read_b128 v[172:175], v247 offset:96
	ds_read_b128 v[224:227], v247 offset:4608
	ds_read_b128 v[228:231], v247 offset:4640
	ds_read_b128 v[232:235], v247 offset:4672
	ds_read_b128 v[236:239], v247 offset:4704
	v_lshl_add_u32 v246, s13, 6, v205
	v_cvt_f32_i32_e32 v246, v246
	v_fma_f32 v242, -v14, v246, -v222
	v_mov_b32_e32 v80, v242
	v_add_f32_e32 v81, v14, v242
	v_fma_f32 v82, v14, s62, v242
	v_fma_f32 v83, v14, s63, v242
	v_fma_f32 v84, v14, s64, v242
	v_fma_f32 v85, v14, s65, v242
	v_fma_f32 v86, v14, s66, v242
	v_fma_f32 v87, v14, s67, v242
	v_fma_f32 v88, v14, s68, v242
	v_fma_f32 v89, v14, s69, v242
	v_fma_f32 v90, v14, s70, v242
	v_fma_f32 v91, v14, s71, v242
	v_fma_f32 v92, v14, s72, v242
	v_fma_f32 v93, v14, s73, v242
	v_fma_f32 v94, v14, s76, v242
	v_fma_f32 v95, v14, s77, v242
	v_fma_f32 v96, v14, s8, v242
	v_fma_f32 v97, v14, s9, v242
	v_fma_f32 v98, v14, s96, v242
	v_fma_f32 v99, v14, s97, v242
	v_fma_f32 v100, v14, s94, v242
	v_fma_f32 v101, v14, s95, v242
	v_fma_f32 v102, v14, s92, v242
	v_fma_f32 v103, v14, s93, v242
	v_fma_f32 v104, v14, s90, v242
	v_fma_f32 v105, v14, s91, v242
	v_fma_f32 v106, v14, s88, v242
	v_fma_f32 v107, v14, s89, v242
	v_fma_f32 v108, v14, s86, v242
	v_fma_f32 v109, v14, s87, v242
	v_fma_f32 v110, v14, s78, v242
	v_fma_f32 v111, v14, s79, v242
	s_waitcnt lgkmcnt(0)
	v_mfma_f32_32x32x16_bf16 v[80:95], v[160:163], v[2:5], v[80:95]
	v_mfma_f32_32x32x16_bf16 v[96:111], v[224:227], v[2:5], v[96:111]
	v_mfma_f32_32x32x16_bf16 v[80:95], v[164:167], v[6:9], v[80:95]
	v_mfma_f32_32x32x16_bf16 v[96:111], v[228:231], v[6:9], v[96:111]
	v_mfma_f32_32x32x16_bf16 v[80:95], v[168:171], v[10:13], v[80:95]
	v_mfma_f32_32x32x16_bf16 v[96:111], v[232:235], v[10:13], v[96:111]
	v_mfma_f32_32x32x16_bf16 v[80:95], v[172:175], v[144:147], v[80:95]
	v_mfma_f32_32x32x16_bf16 v[96:111], v[236:239], v[144:147], v[96:111]

; #define ATT_LSTORE(buf) do { LAS unsigned char* b_ = lds + (buf) * BUF; \
;         _Pragma("unroll") for (int i = 0; i < KPT; ++i) { if (KCH % NTHREADS == 0 || tid + i * NTHREADS < KCH) *(LAS u32x4*)(b_ + klo[i]) = kreg[i]; } \
;         _Pragma("unroll") for (int i = 0; i < VPT; ++i) *(LAS u32x4*)(b_ + vlo[i]) = vreg[i]; } while (0)
; template <int DQK, int DV, int FLAGS, int qp, int kp, int vts, int op> ...
;     ...
;     for (int it = 0; it < ntile; ++it) {
;         const int t = (FLAGS & AF_REV) ? kt_hi - 1 - it : kt_lo + it;
;         const int cur = it & 1;
;         const bool more = (it + 1 < ntile);
;         const int kv0 = t * 64;
;     ...
;         if (more) ATT_LSTORE(cur ^ 1);
;         __syncthreads();
.Ld_nopre_q3:
.Ld_tail3:
	s_add_i32 s23, s23, 1
	s_cmp_ge_i32 s23, s3
	s_cbranch_scc1 .Ld_flush0
	s_waitcnt lgkmcnt(0)
	s_barrier
	s_branch .Ld_top0
